# MLA main loop: waves 4-7 rendezvous after 12 of the 16 second-half exps instead of 8
# speedup vs baseline: 1.0068x; 1.0015x over previous
.LBB0_365:
	v_exp_f32_e32 v48, v48
	v_exp_f32_e32 v49, v49
	v_exp_f32_e32 v50, v50
	v_exp_f32_e32 v51, v51
	v_exp_f32_e32 v52, v52
	v_exp_f32_e32 v53, v53
	v_exp_f32_e32 v54, v54
	v_exp_f32_e32 v55, v55
	v_exp_f32_e32 v56, v56
	v_exp_f32_e32 v57, v57
	v_exp_f32_e32 v58, v58
	v_exp_f32_e32 v59, v59
	s_cmp_eq_u32 s98, 0
	s_cbranch_scc1 .Lstg_x_11
	s_waitcnt lgkmcnt(0)
	s_barrier
.Lstg_x_11:
	v_exp_f32_e32 v219, v60
	v_exp_f32_e32 v220, v61
	v_exp_f32_e32 v221, v62
	v_exp_f32_e32 v222, v63
	v_cvt_pk_bf16_f32 v224, v64, v65
	v_cvt_pk_bf16_f32 v225, v66, v67
	v_cvt_pk_bf16_f32 v226, v68, v69
	v_cvt_pk_bf16_f32 v227, v70, v71
	v_cvt_pk_bf16_f32 v228, v72, v73
	v_cvt_pk_bf16_f32 v229, v74, v75
	v_cvt_pk_bf16_f32 v230, v76, v77
	v_cvt_pk_bf16_f32 v231, v78, v79
	v_cvt_pk_bf16_f32 v232, v48, v49
	v_cvt_pk_bf16_f32 v233, v50, v51
	v_cvt_pk_bf16_f32 v234, v52, v53
	v_cvt_pk_bf16_f32 v235, v54, v55
	v_cvt_pk_bf16_f32 v236, v56, v57
	v_cvt_pk_bf16_f32 v237, v58, v59
	v_cvt_pk_bf16_f32 v238, v219, v220
	v_cvt_pk_bf16_f32 v239, v221, v222
	s_setprio 1
	s_cmp_lg_u32 s98, 0
	s_cbranch_scc1 .Lstg_y_12
	s_waitcnt lgkmcnt(0)
	s_barrier
